# P3 GLA scan rewritten: q/scores/k staged by LDS-DMA into unpadded XOR-swizzled 3-deep LDS ring (conflict-free ds_read_b128), +16KB static LDS
# baseline (speedup 1.0000x reference)
; #define LAS __attribute__((address_space(3)))
; __device__ __forceinline__ void gla_scan_item(const Ctx& C, int item, LAS unsigned char* lds, int tid) {
;     const int jx = item >> 3, bh = (item & 7) * 4 + (jx >> 3), sl = jx & 7, b = bh >> 2, h = bh & 3;
;     LAS bf16* Aq = (LAS bf16*)lds;
;     LAS bf16* Bc = (LAS bf16*)(lds + 25600);
;     LAS bf16* Kt = (LAS bf16*)(lds + 38400);
;     const int wave = tid >> 6, lane = tid & 63, l15 = lane & 15, quad = lane >> 4;
;     f32x4 S[2] = {(f32x4){0.f, 0.f, 0.f, 0.f}, (f32x4){0.f, 0.f, 0.f, 0.f}};
;     *(LAS u32x4*)(Bc + (tid >> 4) * 200 + (tid & 15) * 8) = (u32x4){0u, 0u, 0u, 0u};
;     u32x4 rq0A, rq1A, rsA, rk0A, rk1A, rvA = (u32x4){0u, 0u, 0u, 0u}; f32x4 rdA;
;     u32x4 rq0B, rq1B, rsB, rk0B, rk1B, rvB = (u32x4){0u, 0u, 0u, 0u}; f32x4 rdB;
.LBB0_428:
	s_cmp_lt_i32 s96, 4
	s_cselect_b64 s[4:5], -1, 0
	s_add_u32 s6, s94, 0xb300000
	s_addc_u32 s7, s95, 0
	s_and_b64 s[0:1], s[4:5], s[0:1]
	s_andn2_b64 vcc, exec, s[0:1]
	s_cbranch_vccnz .LBB0_496
	s_cmpk_gt_i32 s2, 0xff
	s_cbranch_scc1 .LBB0_496
	s_mov_b32 s3, s2
	v_readfirstlane_b32 s32, v163
	v_and_b32_e32 v208, 63, v162
	v_and_b32_e32 v207, 15, v162
	v_bfe_u32 v206, v162, 4, 2
	v_lshrrev_b32_e32 v205, 4, v208
	v_lshl_add_u32 v205, v163, 3, v205
	v_and_b32_e32 v204, 15, v205
	v_xor_b32_e32 v204, v204, v207
	v_lshlrev_b32_e32 v255, 10, v205
	v_lshl_add_u32 v255, v204, 4, v255
	v_lshrrev_b32_e32 v205, 4, v208
	v_lshl_add_u32 v205, v163, 3, v205
	v_add_u32_e32 v205, 4, v205
	v_and_b32_e32 v204, 15, v205
	v_xor_b32_e32 v204, v204, v207
	v_lshlrev_b32_e32 v254, 10, v205
	v_lshl_add_u32 v254, v204, 4, v254
	v_lshrrev_b32_e32 v205, 3, v208
	v_lshl_add_u32 v205, v163, 3, v205
	v_bfe_u32 v204, v205, 1, 3
	v_and_b32_e32 v203, 7, v208
	v_xor_b32_e32 v204, v204, v203
	v_lshlrev_b32_e32 v253, 7, v205
	v_lshl_add_u32 v253, v204, 4, v253
	v_lshrrev_b32_e32 v205, 3, v208
	v_lshl_add_u32 v205, v163, 4, v205
	v_bfe_u32 v204, v205, 1, 3
	v_and_b32_e32 v203, 7, v208
	v_xor_b32_e32 v204, v204, v203
	v_lshlrev_b32_e32 v252, 7, v205
	v_lshl_add_u32 v252, v204, 4, v252
	v_lshrrev_b32_e32 v205, 3, v208
	v_lshl_add_u32 v205, v163, 4, v205
	v_add_u32_e32 v205, 8, v205
	v_bfe_u32 v204, v205, 1, 3
	v_and_b32_e32 v203, 7, v208
	v_xor_b32_e32 v204, v204, v203
	v_lshlrev_b32_e32 v251, 7, v205
	v_lshl_add_u32 v251, v204, 4, v251
	s_lshl_b32 s46, s32, 11
	s_lshl_b32 s47, s32, 10
	s_add_i32 s47, s47, 0x4000
	s_add_i32 s48, s46, 0x6000
	v_lshrrev_b32_e32 v205, 1, v163
	v_lshl_add_u32 v205, v205, 4, v207
	v_or_b32_e32 v204, 0, v206
	v_and_b32_e32 v203, 15, v205
	v_xor_b32_e32 v204, v204, v203
	v_lshlrev_b32_e32 v245, 8, v205
	v_lshl_add_u32 v245, v204, 4, v245
	v_or_b32_e32 v204, 4, v206
	v_and_b32_e32 v203, 15, v205
	v_xor_b32_e32 v204, v204, v203
	v_lshlrev_b32_e32 v244, 8, v205
	v_lshl_add_u32 v244, v204, 4, v244
	v_or_b32_e32 v204, 8, v206
	v_and_b32_e32 v203, 15, v205
	v_xor_b32_e32 v204, v204, v203
	v_lshlrev_b32_e32 v243, 8, v205
	v_lshl_add_u32 v243, v204, 4, v243
	v_or_b32_e32 v204, 12, v206
	v_and_b32_e32 v203, 15, v205
	v_xor_b32_e32 v204, v204, v203
	v_lshlrev_b32_e32 v242, 8, v205
	v_lshl_add_u32 v242, v204, 4, v242
	v_or_b32_e32 v204, 0, v206
	v_bfe_u32 v203, v205, 1, 3
	v_xor_b32_e32 v204, v204, v203
	v_lshlrev_b32_e32 v235, 7, v205
	v_lshl_add_u32 v235, v204, 4, v235
	v_add_u32_e32 v235, 0x4000, v235
	v_or_b32_e32 v204, 4, v206
	v_bfe_u32 v203, v205, 1, 3
	v_xor_b32_e32 v204, v204, v203
	v_lshlrev_b32_e32 v234, 7, v205
	v_lshl_add_u32 v234, v204, 4, v234
	v_add_u32_e32 v234, 0x4000, v234
	v_lshlrev_b32_e32 v248, 11, v205
	v_and_b32_e32 v205, 1, v163
	v_lshl_add_u32 v248, v205, 5, v248
	v_lshl_add_u32 v248, v206, 3, v248
	v_lshl_add_u32 v205, v205, 4, v207
	v_or_b32_e32 v204, 0, v206
	v_and_b32_e32 v203, 15, v205
	v_xor_b32_e32 v204, v204, v203
	v_lshlrev_b32_e32 v227, 8, v205
	v_lshl_add_u32 v227, v204, 4, v227
	v_add_u32_e32 v227, 0x1e000, v227
	v_or_b32_e32 v204, 4, v206
	v_and_b32_e32 v203, 15, v205
	v_xor_b32_e32 v204, v204, v203
	v_lshlrev_b32_e32 v226, 8, v205
	v_lshl_add_u32 v226, v204, 4, v226
	v_add_u32_e32 v226, 0x1e000, v226
	v_or_b32_e32 v204, 8, v206
	v_and_b32_e32 v203, 15, v205
	v_xor_b32_e32 v204, v204, v203
	v_lshlrev_b32_e32 v225, 8, v205
	v_lshl_add_u32 v225, v204, 4, v225
	v_add_u32_e32 v225, 0x1e000, v225
	v_or_b32_e32 v204, 12, v206
	v_and_b32_e32 v203, 15, v205
	v_xor_b32_e32 v204, v204, v203
	v_lshlrev_b32_e32 v224, 8, v205
	v_lshl_add_u32 v224, v204, 4, v224
	v_add_u32_e32 v224, 0x1e000, v224
	v_or_b32_e32 v204, 0, v206
	v_bfe_u32 v203, v205, 1, 3
	v_xor_b32_e32 v204, v204, v203
	v_lshlrev_b32_e32 v223, 7, v205
	v_lshl_add_u32 v223, v204, 4, v223
	v_add_u32_e32 v223, 0x20100, v223
	v_or_b32_e32 v204, 4, v206
	v_bfe_u32 v203, v205, 1, 3
	v_xor_b32_e32 v204, v204, v203
	v_lshlrev_b32_e32 v222, 7, v205
	v_lshl_add_u32 v222, v204, 4, v222
	v_add_u32_e32 v222, 0x20100, v222
	v_lshl_add_u32 v205, v163, 4, v207
	v_or_b32_e32 v204, 0, v206
	v_bfe_u32 v203, v205, 1, 3
	v_xor_b32_e32 v204, v204, v203
	v_lshlrev_b32_e32 v231, 7, v205
	v_lshl_add_u32 v231, v204, 4, v231
	v_add_u32_e32 v231, 0x6000, v231
	v_or_b32_e32 v204, 4, v206
	v_bfe_u32 v203, v205, 1, 3
	v_xor_b32_e32 v204, v204, v203
	v_lshlrev_b32_e32 v230, 7, v205
	v_lshl_add_u32 v230, v204, 4, v230
	v_add_u32_e32 v230, 0x6000, v230
	v_mov_b32_e32 v205, v207
	v_or_b32_e32 v204, 0, v206
	v_bfe_u32 v203, v205, 1, 3
	v_xor_b32_e32 v204, v204, v203
	v_lshlrev_b32_e32 v221, 7, v205
	v_lshl_add_u32 v221, v204, 4, v221
	v_add_u32_e32 v221, 0x20100, v221
	v_or_b32_e32 v204, 4, v206
	v_bfe_u32 v203, v205, 1, 3
	v_xor_b32_e32 v204, v204, v203
	v_lshlrev_b32_e32 v220, 7, v205
	v_lshl_add_u32 v220, v204, 4, v220
	v_add_u32_e32 v220, 0x20100, v220
	v_add_u32_e32 v205, 16, v207
	v_or_b32_e32 v204, 0, v206
	v_bfe_u32 v203, v205, 1, 3
	v_xor_b32_e32 v204, v204, v203
	v_lshlrev_b32_e32 v219, 7, v205
	v_lshl_add_u32 v219, v204, 4, v219
	v_add_u32_e32 v219, 0x20100, v219
	v_or_b32_e32 v204, 4, v206
	v_bfe_u32 v203, v205, 1, 3
	v_xor_b32_e32 v204, v204, v203
	v_lshlrev_b32_e32 v218, 7, v205
	v_lshl_add_u32 v218, v204, 4, v218
	v_add_u32_e32 v218, 0x20100, v218
	v_add_u32_e32 v241, 0x14000, v245
	v_add_u32_e32 v240, 0x14000, v244
	v_add_u32_e32 v239, 0x14000, v243
	v_add_u32_e32 v238, 0x14000, v242
	v_add_u32_e32 v233, 0x14000, v235
	v_add_u32_e32 v232, 0x14000, v234
	v_add_u32_e32 v229, 0x14000, v231
	v_add_u32_e32 v228, 0x14000, v230
	v_lshrrev_b32_e32 v204, 1, v206
	v_lshl_add_u32 v204, v163, 1, v204
; #define LAS __attribute__((address_space(3)))
; __device__ __forceinline__ void gla_scan_item(const Ctx& C, int item, LAS unsigned char* lds, int tid) {
;     const int jx = item >> 3, bh = (item & 7) * 4 + (jx >> 3), sl = jx & 7, b = bh >> 2, h = bh & 3;
;     LAS bf16* Aq = (LAS bf16*)lds;
;     LAS bf16* Bc = (LAS bf16*)(lds + 25600);
;     LAS bf16* Kt = (LAS bf16*)(lds + 38400);
;     const int wave = tid >> 6, lane = tid & 63, l15 = lane & 15, quad = lane >> 4;
;     f32x4 S[2] = {(f32x4){0.f, 0.f, 0.f, 0.f}, (f32x4){0.f, 0.f, 0.f, 0.f}};
;     *(LAS u32x4*)(Bc + (tid >> 4) * 200 + (tid & 15) * 8) = (u32x4){0u, 0u, 0u, 0u};
;     u32x4 rq0A, rq1A, rsA, rk0A, rk1A, rvA = (u32x4){0u, 0u, 0u, 0u}; f32x4 rdA;
;     u32x4 rq0B, rq1B, rsB, rk0B, rk1B, rvB = (u32x4){0u, 0u, 0u, 0u}; f32x4 rdB;
;     ...
;     SCAN_LOAD(A, 0); SCAN_LOAD(B, 1);
	v_xor_b32_e32 v204, v204, v207
	v_lshlrev_b32_e32 v217, 8, v207
	v_lshl_add_u32 v217, v204, 4, v217
	v_and_b32_e32 v204, 1, v206
	v_lshl_add_u32 v217, v204, 3, v217
	v_add_u32_e32 v217, 0x1e000, v217
	v_bfe_u32 v205, v162, 2, 6
	v_and_b32_e32 v203, 3, v162
	v_lshl_add_u32 v204, v203, 3, 0
	v_lshlrev_b32_e32 v216, 7, v204
	v_bfe_u32 v204, v204, 1, 3
	v_lshrrev_b32_e32 v246, 3, v205
	v_xor_b32_e32 v204, v204, v246
	v_lshl_add_u32 v216, v204, 4, v216
	v_and_b32_e32 v204, 7, v205
	v_lshl_add_u32 v216, v204, 1, v216
	v_add_u32_e32 v216, 0x20100, v216
	v_lshl_add_u32 v204, v203, 3, 1
	v_lshlrev_b32_e32 v215, 7, v204
	v_bfe_u32 v204, v204, 1, 3
	v_lshrrev_b32_e32 v246, 3, v205
	v_xor_b32_e32 v204, v204, v246
	v_lshl_add_u32 v215, v204, 4, v215
	v_and_b32_e32 v204, 7, v205
	v_lshl_add_u32 v215, v204, 1, v215
	v_add_u32_e32 v215, 0x20100, v215
	v_lshl_add_u32 v204, v203, 3, 2
	v_lshlrev_b32_e32 v214, 7, v204
	v_bfe_u32 v204, v204, 1, 3
	v_lshrrev_b32_e32 v246, 3, v205
	v_xor_b32_e32 v204, v204, v246
	v_lshl_add_u32 v214, v204, 4, v214
	v_and_b32_e32 v204, 7, v205
	v_lshl_add_u32 v214, v204, 1, v214
	v_add_u32_e32 v214, 0x20100, v214
	v_lshl_add_u32 v204, v203, 3, 3
	v_lshlrev_b32_e32 v213, 7, v204
	v_bfe_u32 v204, v204, 1, 3
	v_lshrrev_b32_e32 v246, 3, v205
	v_xor_b32_e32 v204, v204, v246
	v_lshl_add_u32 v213, v204, 4, v213
	v_and_b32_e32 v204, 7, v205
	v_lshl_add_u32 v213, v204, 1, v213
	v_add_u32_e32 v213, 0x20100, v213
	v_lshl_add_u32 v204, v203, 3, 4
	v_lshlrev_b32_e32 v212, 7, v204
	v_bfe_u32 v204, v204, 1, 3
	v_lshrrev_b32_e32 v246, 3, v205
	v_xor_b32_e32 v204, v204, v246
	v_lshl_add_u32 v212, v204, 4, v212
	v_and_b32_e32 v204, 7, v205
	v_lshl_add_u32 v212, v204, 1, v212
	v_add_u32_e32 v212, 0x20100, v212
	v_lshl_add_u32 v204, v203, 3, 5
	v_lshlrev_b32_e32 v211, 7, v204
	v_bfe_u32 v204, v204, 1, 3
	v_lshrrev_b32_e32 v246, 3, v205
	v_xor_b32_e32 v204, v204, v246
	v_lshl_add_u32 v211, v204, 4, v211
	v_and_b32_e32 v204, 7, v205
	v_lshl_add_u32 v211, v204, 1, v211
	v_add_u32_e32 v211, 0x20100, v211
	v_lshl_add_u32 v204, v203, 3, 6
	v_lshlrev_b32_e32 v210, 7, v204
	v_bfe_u32 v204, v204, 1, 3
	v_lshrrev_b32_e32 v246, 3, v205
	v_xor_b32_e32 v204, v204, v246
	v_lshl_add_u32 v210, v204, 4, v210
	v_and_b32_e32 v204, 7, v205
	v_lshl_add_u32 v210, v204, 1, v210
	v_add_u32_e32 v210, 0x20100, v210
	v_lshl_add_u32 v204, v203, 3, 7
	v_lshlrev_b32_e32 v209, 7, v204
	v_bfe_u32 v204, v204, 1, 3
	v_lshrrev_b32_e32 v246, 3, v205
	v_xor_b32_e32 v204, v204, v246
	v_lshl_add_u32 v209, v204, 4, v209
	v_and_b32_e32 v204, 7, v205
	v_lshl_add_u32 v209, v204, 1, v209
	v_add_u32_e32 v209, 0x20100, v209
	v_bfe_u32 v205, v162, 2, 6
	v_and_b32_e32 v204, 3, v162
	v_lshlrev_b32_e32 v250, 14, v205
	v_lshl_add_u32 v250, v204, 4, v250
	v_lshlrev_b32_e32 v249, 6, v163
	v_lshl_add_u32 v249, v206, 4, v249
	v_lshlrev_b32_e32 v247, 14, v163
	v_lshl_add_u32 v247, v206, 12, v247
	v_lshl_add_u32 v247, v207, 2, v247
	v_lshlrev_b32_e32 v246, 4, v162
	v_add_u32_e32 v246, 0x1e000, v246
	v_mov_b32_e32 v116, 0
	v_mov_b32_e32 v117, 0
	v_mov_b32_e32 v118, 0
	v_mov_b32_e32 v119, 0
.Lp3_item:
	s_lshr_b32 s4, s3, 3
	s_and_b32 s41, s4, 7
	s_lshr_b32 s5, s4, 3
	s_and_b32 s37, s3, 7
	s_lshl_b32 s37, s37, 2
	s_add_i32 s37, s37, s5
	s_lshr_b32 s39, s37, 2
	s_and_b32 s40, s37, 3
	s_add_u32 s8, s94, 0x1d800000
	s_addc_u32 s9, s95, 0
	s_lshl_b32 s31, s39, 21
	s_add_u32 s8, s8, s31
	s_addc_u32 s9, s9, 0
	s_lshl_b32 s31, s40, 8
	s_add_u32 s8, s8, s31
	s_addc_u32 s9, s9, 0
	s_add_u32 s10, s94, 0x2f00000
	s_addc_u32 s11, s95, 0
	s_lshl_b32 s31, s37, 18
	s_add_u32 s10, s10, s31
	s_addc_u32 s11, s11, 0
	s_add_u32 s12, s94, 0x3700000
	s_addc_u32 s13, s95, 0
	s_lshl_b32 s31, s37, 19
	s_add_u32 s12, s12, s31
	s_addc_u32 s13, s13, 0
	s_add_u32 s14, s94, 0xd402000
	s_addc_u32 s15, s95, 0
	s_lshl_b32 s31, s39, 25
	s_add_u32 s14, s14, s31
	s_addc_u32 s15, s15, 0
	s_lshl_b32 s31, s40, 9
	s_add_u32 s14, s14, s31
	s_addc_u32 s15, s15, 0
	s_lshl_b32 s31, s41, 6
	s_add_u32 s14, s14, s31
	s_addc_u32 s15, s15, 0
	s_add_u32 s16, s94, 0x2e00000
	s_addc_u32 s17, s95, 0
	s_lshl_b32 s31, s37, 14
	s_add_u32 s16, s16, s31
	s_addc_u32 s17, s17, 0
	s_add_u32 s18, s6, 0x0
	s_addc_u32 s19, s7, 0
	s_lshl_b32 s31, s39, 22
	s_add_u32 s18, s18, s31
	s_addc_u32 s19, s19, 0
	s_lshl_b32 s31, s40, 9
	s_add_u32 s18, s18, s31
	s_addc_u32 s19, s19, 0
	s_lshl_b32 s31, s41, 6
	s_add_u32 s18, s18, s31
	s_addc_u32 s19, s19, 0
	s_add_u32 s34, s92, 0x4090000
	s_addc_u32 s35, s93, 0
	s_lshl_b32 s31, s37, 17
	s_add_u32 s34, s34, s31
	s_addc_u32 s35, s35, 0
	s_lshl_b32 s31, s41, 7
	s_add_u32 s34, s34, s31
	s_addc_u32 s35, s35, 0
	v_mov_b32_e32 v0, 0
	v_mov_b32_e32 v1, 0
	v_mov_b32_e32 v2, 0
	v_mov_b32_e32 v3, 0
	v_mov_b32_e32 v4, 0
	v_mov_b32_e32 v5, 0
	v_mov_b32_e32 v6, 0
	v_mov_b32_e32 v7, 0
	ds_write_b128 v246, v[116:119]
	s_mov_b32 m0, s46
	s_nop 0
	global_load_lds_dwordx4 v255, s[8:9]
	s_add_i32 m0, s46, 0x400
	s_nop 0
	global_load_lds_dwordx4 v254, s[8:9]
	s_mov_b32 m0, s47
	s_nop 0
	global_load_lds_dwordx4 v253, s[10:11]
	s_mov_b32 m0, s48
	s_nop 0
	global_load_lds_dwordx4 v252, s[12:13]
	s_add_i32 m0, s48, 0x400
	s_nop 0
	global_load_lds_dwordx4 v251, s[12:13]
	s_add_u32 s8, s8, 0x10000
	s_addc_u32 s9, s9, 0
	s_add_u32 s10, s10, 0x2000
	s_addc_u32 s11, s11, 0
	s_add_u32 s12, s12, 0x4000
	s_addc_u32 s13, s13, 0
	s_add_i32 m0, s46, 0xa000
	s_nop 0
	global_load_lds_dwordx4 v255, s[8:9]
	s_add_i32 m0, s46, 0xa400
	s_nop 0
	global_load_lds_dwordx4 v254, s[8:9]
	s_add_i32 m0, s47, 0xa000
	s_nop 0
	global_load_lds_dwordx4 v253, s[10:11]
	s_add_i32 m0, s48, 0xa000
	s_nop 0
	global_load_lds_dwordx4 v252, s[12:13]
	s_add_i32 m0, s48, 0xa400
	s_nop 0
	global_load_lds_dwordx4 v251, s[12:13]
	s_add_u32 s8, s8, 0x10000
	s_addc_u32 s9, s9, 0
	s_add_u32 s10, s10, 0x2000
	s_addc_u32 s11, s11, 0
	s_add_u32 s12, s12, 0x4000
	s_addc_u32 s13, s13, 0
	global_load_dwordx4 v[8:11], v250, s[14:15]
	global_load_dwordx4 v[12:15], v249, s[16:17]
	s_add_u32 s14, s14, 0x100000
	s_addc_u32 s15, s15, 0
	s_add_u32 s16, s16, 0x200
	s_addc_u32 s17, s17, 0
	global_load_dwordx4 v[16:19], v250, s[14:15]
	global_load_dwordx4 v[20:23], v249, s[16:17]
	s_add_u32 s14, s14, 0x100000
	s_addc_u32 s15, s15, 0
	s_add_u32 s16, s16, 0x200
	s_addc_u32 s17, s17, 0
	global_load_dwordx4 v[24:27], v250, s[14:15]
	global_load_dwordx4 v[28:31], v249, s[16:17]
	s_add_u32 s14, s14, 0x100000
	s_addc_u32 s15, s15, 0
	s_add_u32 s16, s16, 0x200
	s_addc_u32 s17, s17, 0
	s_waitcnt vmcnt(0)
	s_cmp_gt_u32 s32, 3
	s_cbranch_scc1 .Lp3_sk1
	ds_write_b16 v216, v8 offset:0
	ds_write_b16_d16_hi v215, v8 offset:0
	ds_write_b16 v214, v9 offset:0
	ds_write_b16_d16_hi v213, v9 offset:0
	ds_write_b16 v212, v10 offset:0
	ds_write_b16_d16_hi v211, v10 offset:0
	ds_write_b16 v210, v11 offset:0
	ds_write_b16_d16_hi v209, v11 offset:0
.Lp3_sk1:
	s_mov_b32 s33, 0
	s_waitcnt lgkmcnt(0)
	s_barrier
.Lp3_loop:
	ds_read_b128 v[80:83], v231 offset:0
	ds_read_b128 v[84:87], v230 offset:0
	ds_read_b128 v[88:91], v221 offset:0
	ds_read_b128 v[92:95], v220 offset:0
	ds_read_b128 v[96:99], v219 offset:0
	ds_read_b128 v[100:103], v218 offset:0
	ds_read_b128 v[32:35], v227 offset:0
	ds_read_b128 v[56:59], v245 offset:0
	ds_read_b128 v[36:39], v226 offset:0
	ds_read_b128 v[60:63], v244 offset:0
	ds_read_b128 v[40:43], v225 offset:0
	ds_read_b128 v[64:67], v243 offset:0
	ds_read_b128 v[44:47], v224 offset:0
	ds_read_b128 v[68:71], v242 offset:0
	ds_read_b128 v[48:51], v223 offset:0
	ds_read_b128 v[72:75], v235 offset:0
	ds_read_b128 v[52:55], v222 offset:0
	ds_read_b128 v[76:79], v234 offset:0
	s_waitcnt vmcnt(10)
	v_pk_mul_f32 v[0:1], v[0:1], v[12:13]
	v_pk_mul_f32 v[2:3], v[2:3], v[14:15]
	v_pk_mul_f32 v[4:5], v[4:5], v[12:13]
	v_pk_mul_f32 v[6:7], v[6:7], v[14:15]
	s_waitcnt lgkmcnt(12)
	v_mfma_f32_16x16x32_bf16 v[0:3], v[80:83], v[88:91], v[0:3]
	v_mfma_f32_16x16x32_bf16 v[4:7], v[80:83], v[96:99], v[4:7]
	v_mfma_f32_16x16x32_bf16 v[0:3], v[84:87], v[92:95], v[0:3]
	v_mfma_f32_16x16x32_bf16 v[4:7], v[84:87], v[100:103], v[4:7]
	s_add_i32 m0, s46, 0x14000
	s_nop 0
	global_load_lds_dwordx4 v255, s[8:9]
	s_add_i32 m0, s46, 0x14400
	s_nop 0
	global_load_lds_dwordx4 v254, s[8:9]
	s_add_i32 m0, s47, 0x14000
	s_nop 0
	global_load_lds_dwordx4 v253, s[10:11]
	s_add_i32 m0, s48, 0x14000
	s_nop 0
	global_load_lds_dwordx4 v252, s[12:13]
	s_add_i32 m0, s48, 0x14400
	s_nop 0
	global_load_lds_dwordx4 v251, s[12:13]
	s_cmp_lt_u32 s33, 29
	s_cselect_b32 s43, 0x10000, 0
	s_add_u32 s8, s8, s43
	s_addc_u32 s9, s9, 0
	s_cmp_lt_u32 s33, 29
	s_cselect_b32 s43, 0x2000, 0
	s_add_u32 s10, s10, s43
	s_addc_u32 s11, s11, 0
	s_cmp_lt_u32 s33, 29
	s_cselect_b32 s43, 0x4000, 0
	s_add_u32 s12, s12, s43
	s_addc_u32 s13, s13, 0
	s_waitcnt lgkmcnt(0)
	v_mfma_f32_16x16x32_bf16 v[104:107], v[32:35], v[56:59], 0
	v_mfma_f32_16x16x32_bf16 v[104:107], v[36:39], v[60:63], v[104:107]
	v_mfma_f32_16x16x32_bf16 v[104:107], v[40:43], v[64:67], v[104:107]
	v_mfma_f32_16x16x32_bf16 v[104:107], v[44:47], v[68:71], v[104:107]
	v_mfma_f32_16x16x32_bf16 v[104:107], v[48:51], v[72:75], v[104:107]
	v_mfma_f32_16x16x32_bf16 v[104:107], v[52:55], v[76:79], v[104:107]
	v_cvt_pk_bf16_f32 v108, v0, v1
	v_cvt_pk_bf16_f32 v109, v2, v3
	v_cvt_pk_bf16_f32 v110, v4, v5
	v_cvt_pk_bf16_f32 v111, v6, v7
	ds_write_b64 v217, v[108:109] offset:12544
	ds_write_b64 v217, v[110:111] offset:16640
	s_cmp_gt_u32 s32, 3
	s_cbranch_scc1 .Lp3_sk2
	ds_write_b16 v216, v16 offset:12288
	ds_write_b16_d16_hi v215, v16 offset:12288
	ds_write_b16 v214, v17 offset:12288
	ds_write_b16_d16_hi v213, v17 offset:12288
	ds_write_b16 v212, v18 offset:12288
	ds_write_b16_d16_hi v211, v18 offset:12288
	ds_write_b16 v210, v19 offset:12288
	ds_write_b16_d16_hi v209, v19 offset:12288
.Lp3_sk2:
	global_load_dwordx4 v[8:11], v250, s[14:15]
	global_load_dwordx4 v[12:15], v249, s[16:17]
	s_cmp_lt_u32 s33, 28
	s_cselect_b32 s43, 0x100000, 0
	s_add_u32 s14, s14, s43
	s_addc_u32 s15, s15, 0
	s_cmp_lt_u32 s33, 28
	s_cselect_b32 s43, 0x200, 0
	s_add_u32 s16, s16, s43
	s_addc_u32 s17, s17, 0
	v_cvt_pk_bf16_f32 v112, v104, v105
	v_cvt_pk_bf16_f32 v113, v106, v107
	global_store_dwordx2 v248, v[112:113], s[18:19]
	s_add_u32 s18, s18, 0x20000
	s_addc_u32 s19, s19, 0
	s_add_i32 s33, s33, 1
	s_waitcnt vmcnt(11)
	s_waitcnt lgkmcnt(0)
	s_barrier
	ds_read_b128 v[80:83], v231 offset:40960
	ds_read_b128 v[84:87], v230 offset:40960
	ds_read_b128 v[88:91], v221 offset:12288
	ds_read_b128 v[92:95], v220 offset:12288
	ds_read_b128 v[96:99], v219 offset:12288
	ds_read_b128 v[100:103], v218 offset:12288
	ds_read_b128 v[32:35], v227 offset:12544
	ds_read_b128 v[56:59], v245 offset:40960
	ds_read_b128 v[36:39], v226 offset:12544
	ds_read_b128 v[60:63], v244 offset:40960
	ds_read_b128 v[40:43], v225 offset:12544
	ds_read_b128 v[64:67], v243 offset:40960
	ds_read_b128 v[44:47], v224 offset:12544
	ds_read_b128 v[68:71], v242 offset:40960
	ds_read_b128 v[48:51], v223 offset:12288
	ds_read_b128 v[72:75], v235 offset:40960
	ds_read_b128 v[52:55], v222 offset:12288
	ds_read_b128 v[76:79], v234 offset:40960
	s_waitcnt vmcnt(10)
	v_pk_mul_f32 v[0:1], v[0:1], v[20:21]
	v_pk_mul_f32 v[2:3], v[2:3], v[22:23]
	v_pk_mul_f32 v[4:5], v[4:5], v[20:21]
	v_pk_mul_f32 v[6:7], v[6:7], v[22:23]
	s_waitcnt lgkmcnt(12)
	v_mfma_f32_16x16x32_bf16 v[0:3], v[80:83], v[88:91], v[0:3]
	v_mfma_f32_16x16x32_bf16 v[4:7], v[80:83], v[96:99], v[4:7]
	v_mfma_f32_16x16x32_bf16 v[0:3], v[84:87], v[92:95], v[0:3]
	v_mfma_f32_16x16x32_bf16 v[4:7], v[84:87], v[100:103], v[4:7]
	s_mov_b32 m0, s46
	s_nop 0
	global_load_lds_dwordx4 v255, s[8:9]
	s_add_i32 m0, s46, 0x400
	s_nop 0
	global_load_lds_dwordx4 v254, s[8:9]
	s_mov_b32 m0, s47
	s_nop 0
	global_load_lds_dwordx4 v253, s[10:11]
	s_mov_b32 m0, s48
	s_nop 0
	global_load_lds_dwordx4 v252, s[12:13]
	s_add_i32 m0, s48, 0x400
	s_nop 0
	global_load_lds_dwordx4 v251, s[12:13]
	s_cmp_lt_u32 s33, 29
	s_cselect_b32 s43, 0x10000, 0
	s_add_u32 s8, s8, s43
	s_addc_u32 s9, s9, 0
	s_cmp_lt_u32 s33, 29
	s_cselect_b32 s43, 0x2000, 0
	s_add_u32 s10, s10, s43
	s_addc_u32 s11, s11, 0
	s_cmp_lt_u32 s33, 29
	s_cselect_b32 s43, 0x4000, 0
	s_add_u32 s12, s12, s43
	s_addc_u32 s13, s13, 0
	s_waitcnt lgkmcnt(0)
	v_mfma_f32_16x16x32_bf16 v[104:107], v[32:35], v[56:59], 0
	v_mfma_f32_16x16x32_bf16 v[104:107], v[36:39], v[60:63], v[104:107]
	v_mfma_f32_16x16x32_bf16 v[104:107], v[40:43], v[64:67], v[104:107]
	v_mfma_f32_16x16x32_bf16 v[104:107], v[44:47], v[68:71], v[104:107]
	v_mfma_f32_16x16x32_bf16 v[104:107], v[48:51], v[72:75], v[104:107]
	v_mfma_f32_16x16x32_bf16 v[104:107], v[52:55], v[76:79], v[104:107]
	v_cvt_pk_bf16_f32 v108, v0, v1
	v_cvt_pk_bf16_f32 v109, v2, v3
	v_cvt_pk_bf16_f32 v110, v4, v5
	v_cvt_pk_bf16_f32 v111, v6, v7
	ds_write_b64 v217, v[108:109] offset:0
	ds_write_b64 v217, v[110:111] offset:4096
	s_cmp_gt_u32 s32, 3
	s_cbranch_scc1 .Lp3_sk3
	ds_write_b16 v216, v24 offset:0
	ds_write_b16_d16_hi v215, v24 offset:0
	ds_write_b16 v214, v25 offset:0
	ds_write_b16_d16_hi v213, v25 offset:0
	ds_write_b16 v212, v26 offset:0
	ds_write_b16_d16_hi v211, v26 offset:0
	ds_write_b16 v210, v27 offset:0
	ds_write_b16_d16_hi v209, v27 offset:0
.Lp3_sk3:
	global_load_dwordx4 v[16:19], v250, s[14:15]
	global_load_dwordx4 v[20:23], v249, s[16:17]
	s_cmp_lt_u32 s33, 28
	s_cselect_b32 s43, 0x100000, 0
	s_add_u32 s14, s14, s43
	s_addc_u32 s15, s15, 0
	s_cmp_lt_u32 s33, 28
	s_cselect_b32 s43, 0x200, 0
	s_add_u32 s16, s16, s43
	s_addc_u32 s17, s17, 0
	v_cvt_pk_bf16_f32 v112, v104, v105
	v_cvt_pk_bf16_f32 v113, v106, v107
	global_store_dwordx2 v248, v[112:113], s[18:19]
	s_add_u32 s18, s18, 0x20000
	s_addc_u32 s19, s19, 0
	s_add_i32 s33, s33, 1
	s_waitcnt vmcnt(11)
	s_waitcnt lgkmcnt(0)
	s_barrier
	ds_read_b128 v[80:83], v229 offset:0
	ds_read_b128 v[84:87], v228 offset:0
	ds_read_b128 v[88:91], v221 offset:0
	ds_read_b128 v[92:95], v220 offset:0
	ds_read_b128 v[96:99], v219 offset:0
	ds_read_b128 v[100:103], v218 offset:0
	ds_read_b128 v[32:35], v227 offset:0
	ds_read_b128 v[56:59], v241 offset:0
	ds_read_b128 v[36:39], v226 offset:0
	ds_read_b128 v[60:63], v240 offset:0
	ds_read_b128 v[40:43], v225 offset:0
	ds_read_b128 v[64:67], v239 offset:0
	ds_read_b128 v[44:47], v224 offset:0
	ds_read_b128 v[68:71], v238 offset:0
	ds_read_b128 v[48:51], v223 offset:0
	ds_read_b128 v[72:75], v233 offset:0
	ds_read_b128 v[52:55], v222 offset:0
	ds_read_b128 v[76:79], v232 offset:0
	s_waitcnt vmcnt(10)
	v_pk_mul_f32 v[0:1], v[0:1], v[28:29]
	v_pk_mul_f32 v[2:3], v[2:3], v[30:31]
	v_pk_mul_f32 v[4:5], v[4:5], v[28:29]
	v_pk_mul_f32 v[6:7], v[6:7], v[30:31]
	s_waitcnt lgkmcnt(12)
	v_mfma_f32_16x16x32_bf16 v[0:3], v[80:83], v[88:91], v[0:3]
	v_mfma_f32_16x16x32_bf16 v[4:7], v[80:83], v[96:99], v[4:7]
	v_mfma_f32_16x16x32_bf16 v[0:3], v[84:87], v[92:95], v[0:3]
	v_mfma_f32_16x16x32_bf16 v[4:7], v[84:87], v[100:103], v[4:7]
	s_add_i32 m0, s46, 0xa000
	s_nop 0
	global_load_lds_dwordx4 v255, s[8:9]
	s_add_i32 m0, s46, 0xa400
	s_nop 0
	global_load_lds_dwordx4 v254, s[8:9]
	s_add_i32 m0, s47, 0xa000
	s_nop 0
	global_load_lds_dwordx4 v253, s[10:11]
	s_add_i32 m0, s48, 0xa000
	s_nop 0
	global_load_lds_dwordx4 v252, s[12:13]
	s_add_i32 m0, s48, 0xa400
	s_nop 0
	global_load_lds_dwordx4 v251, s[12:13]
	s_cmp_lt_u32 s33, 29
	s_cselect_b32 s43, 0x10000, 0
	s_add_u32 s8, s8, s43
	s_addc_u32 s9, s9, 0
	s_cmp_lt_u32 s33, 29
	s_cselect_b32 s43, 0x2000, 0
	s_add_u32 s10, s10, s43
	s_addc_u32 s11, s11, 0
	s_cmp_lt_u32 s33, 29
	s_cselect_b32 s43, 0x4000, 0
	s_add_u32 s12, s12, s43
	s_addc_u32 s13, s13, 0
	s_waitcnt lgkmcnt(0)
	v_mfma_f32_16x16x32_bf16 v[104:107], v[32:35], v[56:59], 0
	v_mfma_f32_16x16x32_bf16 v[104:107], v[36:39], v[60:63], v[104:107]
	v_mfma_f32_16x16x32_bf16 v[104:107], v[40:43], v[64:67], v[104:107]
	v_mfma_f32_16x16x32_bf16 v[104:107], v[44:47], v[68:71], v[104:107]
	v_mfma_f32_16x16x32_bf16 v[104:107], v[48:51], v[72:75], v[104:107]
	v_mfma_f32_16x16x32_bf16 v[104:107], v[52:55], v[76:79], v[104:107]
	v_cvt_pk_bf16_f32 v108, v0, v1
	v_cvt_pk_bf16_f32 v109, v2, v3
	v_cvt_pk_bf16_f32 v110, v4, v5
	v_cvt_pk_bf16_f32 v111, v6, v7
	ds_write_b64 v217, v[108:109] offset:12544
	ds_write_b64 v217, v[110:111] offset:16640
	s_cmp_gt_u32 s32, 3
	s_cbranch_scc1 .Lp3_sk4
	ds_write_b16 v216, v8 offset:12288
	ds_write_b16_d16_hi v215, v8 offset:12288
	ds_write_b16 v214, v9 offset:12288
	ds_write_b16_d16_hi v213, v9 offset:12288
	ds_write_b16 v212, v10 offset:12288
	ds_write_b16_d16_hi v211, v10 offset:12288
	ds_write_b16 v210, v11 offset:12288
	ds_write_b16_d16_hi v209, v11 offset:12288
.Lp3_sk4:
	global_load_dwordx4 v[24:27], v250, s[14:15]
	global_load_dwordx4 v[28:31], v249, s[16:17]
	s_cmp_lt_u32 s33, 28
	s_cselect_b32 s43, 0x100000, 0
	s_add_u32 s14, s14, s43
	s_addc_u32 s15, s15, 0
	s_cmp_lt_u32 s33, 28
	s_cselect_b32 s43, 0x200, 0
	s_add_u32 s16, s16, s43
	s_addc_u32 s17, s17, 0
	v_cvt_pk_bf16_f32 v112, v104, v105
	v_cvt_pk_bf16_f32 v113, v106, v107
	global_store_dwordx2 v248, v[112:113], s[18:19]
	s_add_u32 s18, s18, 0x20000
	s_addc_u32 s19, s19, 0
	s_add_i32 s33, s33, 1
	s_waitcnt vmcnt(11)
	s_waitcnt lgkmcnt(0)
	s_barrier
	ds_read_b128 v[80:83], v231 offset:0
	ds_read_b128 v[84:87], v230 offset:0
	ds_read_b128 v[88:91], v221 offset:12288
	ds_read_b128 v[92:95], v220 offset:12288
	ds_read_b128 v[96:99], v219 offset:12288
	ds_read_b128 v[100:103], v218 offset:12288
	ds_read_b128 v[32:35], v227 offset:12544
	ds_read_b128 v[56:59], v245 offset:0
	ds_read_b128 v[36:39], v226 offset:12544
	ds_read_b128 v[60:63], v244 offset:0
	ds_read_b128 v[40:43], v225 offset:12544
	ds_read_b128 v[64:67], v243 offset:0
	ds_read_b128 v[44:47], v224 offset:12544
	ds_read_b128 v[68:71], v242 offset:0
	ds_read_b128 v[48:51], v223 offset:12288
	ds_read_b128 v[72:75], v235 offset:0
	ds_read_b128 v[52:55], v222 offset:12288
	ds_read_b128 v[76:79], v234 offset:0
	s_waitcnt vmcnt(10)
	v_pk_mul_f32 v[0:1], v[0:1], v[12:13]
	v_pk_mul_f32 v[2:3], v[2:3], v[14:15]
	v_pk_mul_f32 v[4:5], v[4:5], v[12:13]
	v_pk_mul_f32 v[6:7], v[6:7], v[14:15]
	s_waitcnt lgkmcnt(12)
	v_mfma_f32_16x16x32_bf16 v[0:3], v[80:83], v[88:91], v[0:3]
	v_mfma_f32_16x16x32_bf16 v[4:7], v[80:83], v[96:99], v[4:7]
	v_mfma_f32_16x16x32_bf16 v[0:3], v[84:87], v[92:95], v[0:3]
	v_mfma_f32_16x16x32_bf16 v[4:7], v[84:87], v[100:103], v[4:7]
	s_add_i32 m0, s46, 0x14000
	s_nop 0
	global_load_lds_dwordx4 v255, s[8:9]
	s_add_i32 m0, s46, 0x14400
	s_nop 0
	global_load_lds_dwordx4 v254, s[8:9]
	s_add_i32 m0, s47, 0x14000
	s_nop 0
	global_load_lds_dwordx4 v253, s[10:11]
	s_add_i32 m0, s48, 0x14000
	s_nop 0
	global_load_lds_dwordx4 v252, s[12:13]
	s_add_i32 m0, s48, 0x14400
	s_nop 0
	global_load_lds_dwordx4 v251, s[12:13]
	s_cmp_lt_u32 s33, 29
	s_cselect_b32 s43, 0x10000, 0
	s_add_u32 s8, s8, s43
	s_addc_u32 s9, s9, 0
	s_cmp_lt_u32 s33, 29
	s_cselect_b32 s43, 0x2000, 0
	s_add_u32 s10, s10, s43
	s_addc_u32 s11, s11, 0
	s_cmp_lt_u32 s33, 29
	s_cselect_b32 s43, 0x4000, 0
	s_add_u32 s12, s12, s43
	s_addc_u32 s13, s13, 0
	s_waitcnt lgkmcnt(0)
	v_mfma_f32_16x16x32_bf16 v[104:107], v[32:35], v[56:59], 0
	v_mfma_f32_16x16x32_bf16 v[104:107], v[36:39], v[60:63], v[104:107]
	v_mfma_f32_16x16x32_bf16 v[104:107], v[40:43], v[64:67], v[104:107]
	v_mfma_f32_16x16x32_bf16 v[104:107], v[44:47], v[68:71], v[104:107]
	v_mfma_f32_16x16x32_bf16 v[104:107], v[48:51], v[72:75], v[104:107]
	v_mfma_f32_16x16x32_bf16 v[104:107], v[52:55], v[76:79], v[104:107]
	v_cvt_pk_bf16_f32 v108, v0, v1
	v_cvt_pk_bf16_f32 v109, v2, v3
	v_cvt_pk_bf16_f32 v110, v4, v5
	v_cvt_pk_bf16_f32 v111, v6, v7
	ds_write_b64 v217, v[108:109] offset:0
	ds_write_b64 v217, v[110:111] offset:4096
	s_cmp_gt_u32 s32, 3
	s_cbranch_scc1 .Lp3_sk5
	ds_write_b16 v216, v16 offset:0
	ds_write_b16_d16_hi v215, v16 offset:0
	ds_write_b16 v214, v17 offset:0
	ds_write_b16_d16_hi v213, v17 offset:0
	ds_write_b16 v212, v18 offset:0
	ds_write_b16_d16_hi v211, v18 offset:0
	ds_write_b16 v210, v19 offset:0
	ds_write_b16_d16_hi v209, v19 offset:0
.Lp3_sk5:
	global_load_dwordx4 v[8:11], v250, s[14:15]
	global_load_dwordx4 v[12:15], v249, s[16:17]
	s_cmp_lt_u32 s33, 28
	s_cselect_b32 s43, 0x100000, 0
	s_add_u32 s14, s14, s43
	s_addc_u32 s15, s15, 0
	s_cmp_lt_u32 s33, 28
	s_cselect_b32 s43, 0x200, 0
	s_add_u32 s16, s16, s43
	s_addc_u32 s17, s17, 0
	v_cvt_pk_bf16_f32 v112, v104, v105
	v_cvt_pk_bf16_f32 v113, v106, v107
	global_store_dwordx2 v248, v[112:113], s[18:19]
	s_add_u32 s18, s18, 0x20000
	s_addc_u32 s19, s19, 0
	s_add_i32 s33, s33, 1
	s_waitcnt vmcnt(11)
	s_waitcnt lgkmcnt(0)
	s_barrier
	ds_read_b128 v[80:83], v231 offset:40960
	ds_read_b128 v[84:87], v230 offset:40960
	ds_read_b128 v[88:91], v221 offset:0
	ds_read_b128 v[92:95], v220 offset:0
	ds_read_b128 v[96:99], v219 offset:0
	ds_read_b128 v[100:103], v218 offset:0
	ds_read_b128 v[32:35], v227 offset:0
	ds_read_b128 v[56:59], v245 offset:40960
	ds_read_b128 v[36:39], v226 offset:0
	ds_read_b128 v[60:63], v244 offset:40960
	ds_read_b128 v[40:43], v225 offset:0
	ds_read_b128 v[64:67], v243 offset:40960
	ds_read_b128 v[44:47], v224 offset:0
	ds_read_b128 v[68:71], v242 offset:40960
	ds_read_b128 v[48:51], v223 offset:0
	ds_read_b128 v[72:75], v235 offset:40960
	ds_read_b128 v[52:55], v222 offset:0
	ds_read_b128 v[76:79], v234 offset:40960
	s_waitcnt vmcnt(10)
	v_pk_mul_f32 v[0:1], v[0:1], v[20:21]
	v_pk_mul_f32 v[2:3], v[2:3], v[22:23]
	v_pk_mul_f32 v[4:5], v[4:5], v[20:21]
	v_pk_mul_f32 v[6:7], v[6:7], v[22:23]
	s_waitcnt lgkmcnt(12)
	v_mfma_f32_16x16x32_bf16 v[0:3], v[80:83], v[88:91], v[0:3]
	v_mfma_f32_16x16x32_bf16 v[4:7], v[80:83], v[96:99], v[4:7]
	v_mfma_f32_16x16x32_bf16 v[0:3], v[84:87], v[92:95], v[0:3]
	v_mfma_f32_16x16x32_bf16 v[4:7], v[84:87], v[100:103], v[4:7]
	s_mov_b32 m0, s46
	s_nop 0
	global_load_lds_dwordx4 v255, s[8:9]
	s_add_i32 m0, s46, 0x400
	s_nop 0
	global_load_lds_dwordx4 v254, s[8:9]
	s_mov_b32 m0, s47
	s_nop 0
	global_load_lds_dwordx4 v253, s[10:11]
	s_mov_b32 m0, s48
	s_nop 0
	global_load_lds_dwordx4 v252, s[12:13]
	s_add_i32 m0, s48, 0x400
	s_nop 0
	global_load_lds_dwordx4 v251, s[12:13]
	s_cmp_lt_u32 s33, 29
	s_cselect_b32 s43, 0x10000, 0
	s_add_u32 s8, s8, s43
	s_addc_u32 s9, s9, 0
	s_cmp_lt_u32 s33, 29
	s_cselect_b32 s43, 0x2000, 0
	s_add_u32 s10, s10, s43
	s_addc_u32 s11, s11, 0
	s_cmp_lt_u32 s33, 29
	s_cselect_b32 s43, 0x4000, 0
	s_add_u32 s12, s12, s43
	s_addc_u32 s13, s13, 0
	s_waitcnt lgkmcnt(0)
	v_mfma_f32_16x16x32_bf16 v[104:107], v[32:35], v[56:59], 0
	v_mfma_f32_16x16x32_bf16 v[104:107], v[36:39], v[60:63], v[104:107]
	v_mfma_f32_16x16x32_bf16 v[104:107], v[40:43], v[64:67], v[104:107]
	v_mfma_f32_16x16x32_bf16 v[104:107], v[44:47], v[68:71], v[104:107]
	v_mfma_f32_16x16x32_bf16 v[104:107], v[48:51], v[72:75], v[104:107]
	v_mfma_f32_16x16x32_bf16 v[104:107], v[52:55], v[76:79], v[104:107]
	v_cvt_pk_bf16_f32 v108, v0, v1
	v_cvt_pk_bf16_f32 v109, v2, v3
	v_cvt_pk_bf16_f32 v110, v4, v5
	v_cvt_pk_bf16_f32 v111, v6, v7
	ds_write_b64 v217, v[108:109] offset:12544
	ds_write_b64 v217, v[110:111] offset:16640
	s_cmp_gt_u32 s32, 3
	s_cbranch_scc1 .Lp3_sk6
	ds_write_b16 v216, v24 offset:12288
	ds_write_b16_d16_hi v215, v24 offset:12288
	ds_write_b16 v214, v25 offset:12288
	ds_write_b16_d16_hi v213, v25 offset:12288
	ds_write_b16 v212, v26 offset:12288
	ds_write_b16_d16_hi v211, v26 offset:12288
	ds_write_b16 v210, v27 offset:12288
	ds_write_b16_d16_hi v209, v27 offset:12288
.Lp3_sk6:
	global_load_dwordx4 v[16:19], v250, s[14:15]
	global_load_dwordx4 v[20:23], v249, s[16:17]
	s_cmp_lt_u32 s33, 28
	s_cselect_b32 s43, 0x100000, 0
	s_add_u32 s14, s14, s43
	s_addc_u32 s15, s15, 0
	s_cmp_lt_u32 s33, 28
	s_cselect_b32 s43, 0x200, 0
	s_add_u32 s16, s16, s43
	s_addc_u32 s17, s17, 0
	v_cvt_pk_bf16_f32 v112, v104, v105
	v_cvt_pk_bf16_f32 v113, v106, v107
	global_store_dwordx2 v248, v[112:113], s[18:19]
	s_add_u32 s18, s18, 0x20000
	s_addc_u32 s19, s19, 0
	s_add_i32 s33, s33, 1
	s_waitcnt vmcnt(11)
	s_waitcnt lgkmcnt(0)
	s_barrier
	ds_read_b128 v[80:83], v229 offset:0
	ds_read_b128 v[84:87], v228 offset:0
	ds_read_b128 v[88:91], v221 offset:12288
	ds_read_b128 v[92:95], v220 offset:12288
	ds_read_b128 v[96:99], v219 offset:12288
	ds_read_b128 v[100:103], v218 offset:12288
	ds_read_b128 v[32:35], v227 offset:12544
	ds_read_b128 v[56:59], v241 offset:0
	ds_read_b128 v[36:39], v226 offset:12544
	ds_read_b128 v[60:63], v240 offset:0
	ds_read_b128 v[40:43], v225 offset:12544
	ds_read_b128 v[64:67], v239 offset:0
	ds_read_b128 v[44:47], v224 offset:12544
	ds_read_b128 v[68:71], v238 offset:0
	ds_read_b128 v[48:51], v223 offset:12288
	ds_read_b128 v[72:75], v233 offset:0
	ds_read_b128 v[52:55], v222 offset:12288
	ds_read_b128 v[76:79], v232 offset:0
	s_waitcnt vmcnt(10)
	v_pk_mul_f32 v[0:1], v[0:1], v[28:29]
	v_pk_mul_f32 v[2:3], v[2:3], v[30:31]
	v_pk_mul_f32 v[4:5], v[4:5], v[28:29]
	v_pk_mul_f32 v[6:7], v[6:7], v[30:31]
	s_waitcnt lgkmcnt(12)
	v_mfma_f32_16x16x32_bf16 v[0:3], v[80:83], v[88:91], v[0:3]
	v_mfma_f32_16x16x32_bf16 v[4:7], v[80:83], v[96:99], v[4:7]
	v_mfma_f32_16x16x32_bf16 v[0:3], v[84:87], v[92:95], v[0:3]
	v_mfma_f32_16x16x32_bf16 v[4:7], v[84:87], v[100:103], v[4:7]
	s_add_i32 m0, s46, 0xa000
	s_nop 0
	global_load_lds_dwordx4 v255, s[8:9]
	s_add_i32 m0, s46, 0xa400
	s_nop 0
	global_load_lds_dwordx4 v254, s[8:9]
	s_add_i32 m0, s47, 0xa000
	s_nop 0
	global_load_lds_dwordx4 v253, s[10:11]
	s_add_i32 m0, s48, 0xa000
	s_nop 0
	global_load_lds_dwordx4 v252, s[12:13]
	s_add_i32 m0, s48, 0xa400
	s_nop 0
	global_load_lds_dwordx4 v251, s[12:13]
	s_cmp_lt_u32 s33, 29
	s_cselect_b32 s43, 0x10000, 0
	s_add_u32 s8, s8, s43
	s_addc_u32 s9, s9, 0
	s_cmp_lt_u32 s33, 29
	s_cselect_b32 s43, 0x2000, 0
	s_add_u32 s10, s10, s43
	s_addc_u32 s11, s11, 0
	s_cmp_lt_u32 s33, 29
	s_cselect_b32 s43, 0x4000, 0
	s_add_u32 s12, s12, s43
	s_addc_u32 s13, s13, 0
	s_waitcnt lgkmcnt(0)
	v_mfma_f32_16x16x32_bf16 v[104:107], v[32:35], v[56:59], 0
	v_mfma_f32_16x16x32_bf16 v[104:107], v[36:39], v[60:63], v[104:107]
	v_mfma_f32_16x16x32_bf16 v[104:107], v[40:43], v[64:67], v[104:107]
	v_mfma_f32_16x16x32_bf16 v[104:107], v[44:47], v[68:71], v[104:107]
	v_mfma_f32_16x16x32_bf16 v[104:107], v[48:51], v[72:75], v[104:107]
	v_mfma_f32_16x16x32_bf16 v[104:107], v[52:55], v[76:79], v[104:107]
	v_cvt_pk_bf16_f32 v108, v0, v1
	v_cvt_pk_bf16_f32 v109, v2, v3
	v_cvt_pk_bf16_f32 v110, v4, v5
	v_cvt_pk_bf16_f32 v111, v6, v7
	ds_write_b64 v217, v[108:109] offset:0
	ds_write_b64 v217, v[110:111] offset:4096
	s_cmp_gt_u32 s32, 3
	s_cbranch_scc1 .Lp3_sk7
	ds_write_b16 v216, v8 offset:0
	ds_write_b16_d16_hi v215, v8 offset:0
	ds_write_b16 v214, v9 offset:0
	ds_write_b16_d16_hi v213, v9 offset:0
	ds_write_b16 v212, v10 offset:0
	ds_write_b16_d16_hi v211, v10 offset:0
	ds_write_b16 v210, v11 offset:0
	ds_write_b16_d16_hi v209, v11 offset:0
; __device__ __forceinline__ void gla_scan_item(const Ctx& C, int item, LAS unsigned char* lds, int tid) {
;     ...
;     SCAN_LOAD(A, 0); SCAN_LOAD(B, 1);
; #pragma unroll
;     for (int n = 0; n < 32; n += 2) { SCAN_STEP(A, n); SCAN_STEP(B, n + 1); }
.Lp3_sk7:
	global_load_dwordx4 v[24:27], v250, s[14:15]
	global_load_dwordx4 v[28:31], v249, s[16:17]
	s_cmp_lt_u32 s33, 28
	s_cselect_b32 s43, 0x100000, 0
	s_add_u32 s14, s14, s43
	s_addc_u32 s15, s15, 0
	s_cmp_lt_u32 s33, 28
	s_cselect_b32 s43, 0x200, 0
	s_add_u32 s16, s16, s43
	s_addc_u32 s17, s17, 0
	v_cvt_pk_bf16_f32 v112, v104, v105
	v_cvt_pk_bf16_f32 v113, v106, v107
	global_store_dwordx2 v248, v[112:113], s[18:19]
	s_add_u32 s18, s18, 0x20000
	s_addc_u32 s19, s19, 0
	s_add_i32 s33, s33, 1
	s_waitcnt vmcnt(11)
	s_waitcnt lgkmcnt(0)
	s_barrier
	s_cmp_lt_u32 s33, 30
	s_cbranch_scc1 .Lp3_loop
	ds_read_b128 v[80:83], v231 offset:0
	ds_read_b128 v[84:87], v230 offset:0
	ds_read_b128 v[88:91], v221 offset:0
	ds_read_b128 v[92:95], v220 offset:0
	ds_read_b128 v[96:99], v219 offset:0
	ds_read_b128 v[100:103], v218 offset:0
	ds_read_b128 v[32:35], v227 offset:0
	ds_read_b128 v[56:59], v245 offset:0
	ds_read_b128 v[36:39], v226 offset:0
	ds_read_b128 v[60:63], v244 offset:0
	ds_read_b128 v[40:43], v225 offset:0
	ds_read_b128 v[64:67], v243 offset:0
	ds_read_b128 v[44:47], v224 offset:0
	ds_read_b128 v[68:71], v242 offset:0
	ds_read_b128 v[48:51], v223 offset:0
	ds_read_b128 v[72:75], v235 offset:0
	ds_read_b128 v[52:55], v222 offset:0
	ds_read_b128 v[76:79], v234 offset:0
	s_waitcnt vmcnt(10)
	v_pk_mul_f32 v[0:1], v[0:1], v[12:13]
	v_pk_mul_f32 v[2:3], v[2:3], v[14:15]
	v_pk_mul_f32 v[4:5], v[4:5], v[12:13]
	v_pk_mul_f32 v[6:7], v[6:7], v[14:15]
	s_waitcnt lgkmcnt(12)
	v_mfma_f32_16x16x32_bf16 v[0:3], v[80:83], v[88:91], v[0:3]
	v_mfma_f32_16x16x32_bf16 v[4:7], v[80:83], v[96:99], v[4:7]
	v_mfma_f32_16x16x32_bf16 v[0:3], v[84:87], v[92:95], v[0:3]
	v_mfma_f32_16x16x32_bf16 v[4:7], v[84:87], v[100:103], v[4:7]
	s_add_i32 m0, s46, 0x14000
	s_nop 0
	global_load_lds_dwordx4 v255, s[8:9]
	s_add_i32 m0, s46, 0x14400
	s_nop 0
	global_load_lds_dwordx4 v254, s[8:9]
	s_add_i32 m0, s47, 0x14000
	s_nop 0
	global_load_lds_dwordx4 v253, s[10:11]
	s_add_i32 m0, s48, 0x14000
	s_nop 0
	global_load_lds_dwordx4 v252, s[12:13]
	s_add_i32 m0, s48, 0x14400
	s_nop 0
	global_load_lds_dwordx4 v251, s[12:13]
	s_cmp_lt_u32 s33, 29
	s_cselect_b32 s43, 0x10000, 0
	s_add_u32 s8, s8, s43
	s_addc_u32 s9, s9, 0
	s_cmp_lt_u32 s33, 29
	s_cselect_b32 s43, 0x2000, 0
	s_add_u32 s10, s10, s43
	s_addc_u32 s11, s11, 0
	s_cmp_lt_u32 s33, 29
	s_cselect_b32 s43, 0x4000, 0
	s_add_u32 s12, s12, s43
	s_addc_u32 s13, s13, 0
	s_waitcnt lgkmcnt(0)
	v_mfma_f32_16x16x32_bf16 v[104:107], v[32:35], v[56:59], 0
	v_mfma_f32_16x16x32_bf16 v[104:107], v[36:39], v[60:63], v[104:107]
	v_mfma_f32_16x16x32_bf16 v[104:107], v[40:43], v[64:67], v[104:107]
	v_mfma_f32_16x16x32_bf16 v[104:107], v[44:47], v[68:71], v[104:107]
	v_mfma_f32_16x16x32_bf16 v[104:107], v[48:51], v[72:75], v[104:107]
	v_mfma_f32_16x16x32_bf16 v[104:107], v[52:55], v[76:79], v[104:107]
	v_cvt_pk_bf16_f32 v108, v0, v1
	v_cvt_pk_bf16_f32 v109, v2, v3
	v_cvt_pk_bf16_f32 v110, v4, v5
	v_cvt_pk_bf16_f32 v111, v6, v7
	ds_write_b64 v217, v[108:109] offset:12544
	ds_write_b64 v217, v[110:111] offset:16640
	s_cmp_gt_u32 s32, 3
	s_cbranch_scc1 .Lp3_sk8
	ds_write_b16 v216, v16 offset:12288
	ds_write_b16_d16_hi v215, v16 offset:12288
	ds_write_b16 v214, v17 offset:12288
	ds_write_b16_d16_hi v213, v17 offset:12288
	ds_write_b16 v212, v18 offset:12288
	ds_write_b16_d16_hi v211, v18 offset:12288
	ds_write_b16 v210, v19 offset:12288
	ds_write_b16_d16_hi v209, v19 offset:12288

; __device__ __forceinline__ void gla_scan_item(const Ctx& C, int item, LAS unsigned char* lds, int tid) {
;     ...
;     SCAN_LOAD(A, 0); SCAN_LOAD(B, 1);
; #pragma unroll
;     for (int n = 0; n < 32; n += 2) { SCAN_STEP(A, n); SCAN_STEP(B, n + 1); }
;     ...
;     float* So = C.out + OUT_GLAP + ((size_t)bh * 128 + wave * 16 + quad * 4) * 256 + sl * 32 + l15;
; #pragma unroll
;     for (int v2 = 0; v2 < 2; ++v2)
; #pragma unroll
;         for (int j = 0; j < 4; ++j) So[(size_t)j * 256 + v2 * 16] = S[v2][j];
;     __syncthreads();
.Lp3_sk9:
	global_load_dwordx4 v[16:19], v250, s[14:15]
	global_load_dwordx4 v[20:23], v249, s[16:17]
	s_cmp_lt_u32 s33, 28
	s_cselect_b32 s43, 0x100000, 0
	s_add_u32 s14, s14, s43
	s_addc_u32 s15, s15, 0
	s_cmp_lt_u32 s33, 28
	s_cselect_b32 s43, 0x200, 0
	s_add_u32 s16, s16, s43
	s_addc_u32 s17, s17, 0
	v_cvt_pk_bf16_f32 v112, v104, v105
	v_cvt_pk_bf16_f32 v113, v106, v107
	global_store_dwordx2 v248, v[112:113], s[18:19]
	s_add_u32 s18, s18, 0x20000
	s_addc_u32 s19, s19, 0
	s_add_i32 s33, s33, 1
	s_waitcnt vmcnt(11)
	s_waitcnt lgkmcnt(0)
	s_barrier
	s_nop 7
	global_store_dword v247, v0, s[34:35] offset:0
	global_store_dword v247, v1, s[34:35] offset:1024
	global_store_dword v247, v2, s[34:35] offset:2048
	global_store_dword v247, v3, s[34:35] offset:3072
	global_store_dword v247, v4, s[34:35] offset:64
	global_store_dword v247, v5, s[34:35] offset:1088
	global_store_dword v247, v6, s[34:35] offset:2112
	global_store_dword v247, v7, s[34:35] offset:3136
	s_waitcnt vmcnt(0) lgkmcnt(0)
	s_barrier
	s_add_i32 s3, s3, s42
	s_cmpk_lt_i32 s3, 0x100
	s_cbranch_scc1 .Lp3_item

; #define LAS __attribute__((address_space(3)))
; __global__ void __launch_bounds__(512, 2) fwd_mega(Args a) {
;     extern __shared__ __attribute__((aligned(16))) unsigned char lds_raw[];
;     LAS unsigned char* lds = (LAS unsigned char*)lds_raw;
	.amdhsa_kernel _Z8fwd_mega4Args
		.amdhsa_group_segment_fixed_size 16384
		.amdhsa_private_segment_fixed_size 0
		.amdhsa_kernarg_size 472
		.amdhsa_user_sgpr_count 2
		.amdhsa_user_sgpr_dispatch_ptr 0
		.amdhsa_user_sgpr_queue_ptr 0
		.amdhsa_user_sgpr_kernarg_segment_ptr 1
		.amdhsa_user_sgpr_dispatch_id 0
		.amdhsa_user_sgpr_kernarg_preload_length 0
		.amdhsa_user_sgpr_kernarg_preload_offset 0
		.amdhsa_user_sgpr_private_segment_size 0
		.amdhsa_uses_dynamic_stack 0
		.amdhsa_enable_private_segment 0
		.amdhsa_system_sgpr_workgroup_id_x 1
		.amdhsa_system_sgpr_workgroup_id_y 0
		.amdhsa_system_sgpr_workgroup_id_z 0
		.amdhsa_system_sgpr_workgroup_info 0
		.amdhsa_system_vgpr_workitem_id 2
		.amdhsa_next_free_vgpr 256
		.amdhsa_next_free_sgpr 98
		.amdhsa_accum_offset 256
		.amdhsa_reserve_vcc 1
		.amdhsa_float_round_mode_32 0
		.amdhsa_float_round_mode_16_64 0
		.amdhsa_float_denorm_mode_32 3
		.amdhsa_float_denorm_mode_16_64 3
		.amdhsa_dx10_clamp 1
		.amdhsa_ieee_mode 1
		.amdhsa_fp16_overflow 0
		.amdhsa_tg_split 0
		.amdhsa_exception_fp_ieee_invalid_op 0
		.amdhsa_exception_fp_denorm_src 0
		.amdhsa_exception_fp_ieee_div_zero 0
		.amdhsa_exception_fp_ieee_overflow 0
		.amdhsa_exception_fp_ieee_underflow 0
		.amdhsa_exception_fp_ieee_inexact 0
		.amdhsa_exception_int_div_zero 0
	.end_amdhsa_kernel

; #define LAS __attribute__((address_space(3)))
; __global__ void __launch_bounds__(512, 2) fwd_mega(Args a) {
;     extern __shared__ __attribute__((aligned(16))) unsigned char lds_raw[];
;     LAS unsigned char* lds = (LAS unsigned char*)lds_raw;
amdhsa.kernels:
  - .agpr_count:     0
    .args:
      - .offset:         0
        .size:           216
        .value_kind:     by_value
      - .offset:         216
        .size:           4
        .value_kind:     hidden_block_count_x
      - .offset:         220
        .size:           4
        .value_kind:     hidden_block_count_y
      - .offset:         224
        .size:           4
        .value_kind:     hidden_block_count_z
      - .offset:         228
        .size:           2
        .value_kind:     hidden_group_size_x
      - .offset:         230
        .size:           2
        .value_kind:     hidden_group_size_y
      - .offset:         232
        .size:           2
        .value_kind:     hidden_group_size_z
      - .offset:         234
        .size:           2
        .value_kind:     hidden_remainder_x
      - .offset:         236
        .size:           2
        .value_kind:     hidden_remainder_y
      - .offset:         238
        .size:           2
        .value_kind:     hidden_remainder_z
      - .offset:         256
        .size:           8
        .value_kind:     hidden_global_offset_x
      - .offset:         264
        .size:           8
        .value_kind:     hidden_global_offset_y
      - .offset:         272
        .size:           8
        .value_kind:     hidden_global_offset_z
      - .offset:         280
        .size:           2
        .value_kind:     hidden_grid_dims
      - .offset:         304
        .size:           8
        .value_kind:     hidden_multigrid_sync_arg
      - .offset:         336
        .size:           4
        .value_kind:     hidden_dynamic_lds_size
    .group_segment_fixed_size: 16384
    .kernarg_segment_align: 8
    .kernarg_segment_size: 472
    .language:       OpenCL C
    .language_version:
      - 2
      - 0
    .max_flat_workgroup_size: 512
    .name:           _Z8fwd_mega4Args
    .private_segment_fixed_size: 0
    .sgpr_count:     104
    .sgpr_spill_count: 81
    .symbol:         _Z8fwd_mega4Args.kd
    .uniform_work_group_size: 1
    .uses_dynamic_stack: false
    .vgpr_count:     256
    .vgpr_spill_count: 0
    .wavefront_size: 64
